# v26 + final RMSNorm phase hand-rewritten (gain loaded once, 4 rows in flight, counted vmcnt); other grid sizes keep the original loop
# baseline (speedup 1.0000x reference)
; DI int TIDX() { int t = (int)threadIdx.x; asm volatile("" : "+v"(t)); return t; }
; DI void phase_final(const Params& p) {
;   const int lane = TIDX() & 63, wid = TIDX() >> 6;
;   for (int it = blockIdx.x; it < T_ / 8; it += gridDim.x) {
;     const int t = it * 8 + wid; const float rs = rstd_from16((const float*)(p.ws + O_SSQ) + (size_t)t * 16, 1.f / 1024.f);
;     float* xr = p.out + (size_t)t * D_;
; #pragma unroll
;     for (int c = 0; c < 4; ++c) { const int k = c * 256 + lane * 4; const f32x4 v = *(const f32x4*)(xr + k), gv = *(const f32x4*)(p.final_norm + k); *(f32x4*)(xr + k) = v * rs * gv; }
;   }
; }
.LBB0_2232:
	s_or_b64 exec, exec, s[0:1]
	s_waitcnt lgkmcnt(0)
	v_mov_b32_e32 v0, v220
	s_cmpk_gt_i32 s36, 0xfff
	s_barrier
	s_cbranch_scc1 .LBB0_2235
	v_readlane_b32 s0, v241, 0
	v_lshlrev_b32_e32 v0, 4, v0
	v_readlane_b32 s4, v241, 2
	v_ashrrev_i32_e32 v4, 6, v220
	v_readlane_b32 s1, v241, 1
	s_add_u32 s0, s0, 0x9154000
	v_and_b32_e32 v2, 0x3f0, v0
	v_mov_b32_e32 v3, 0
	v_readlane_b32 s5, v241, 3
	v_readlane_b32 s6, v241, 4
	v_readlane_b32 s7, v241, 5
	s_addc_u32 s1, s1, 0
	v_lshl_add_u64 v[0:1], s[4:5], 0, v[2:3]
	v_lshl_add_u64 v[2:3], s[6:7], 0, v[2:3]
	v_lshl_add_u32 v4, s36, 3, v4
	s_lshl_b32 s2, s37, 3
	v_mov_b32_e32 v6, 0x358637bd
	s_mov_b32 s3, 0x800000
	s_cmp_lg_u32 s37, 0x100
	s_cbranch_scc1 .LBB0_2234
	v_lshlrev_b32_e32 v8, 6, v4
	v_mov_b32_e32 v9, 0
	v_lshl_add_u64 v[8:9], s[0:1], 0, v[8:9]
	v_lshlrev_b32_e32 v10, 12, v4
	v_mov_b32_e32 v11, 0
	v_lshl_add_u64 v[10:11], v[2:3], 0, v[10:11]
	v_mov_b32_e32 v12, v10
	v_mov_b32_e32 v13, v11
	s_mov_b32 s98, 0x20000
	s_mov_b32 s99, 0
	s_mov_b32 s100, 0x800000
	s_mov_b32 s101, 0
	global_load_dwordx4 v[48:51], v[0:1], off
	global_load_dwordx4 v[52:55], v[0:1], off offset:1024
	global_load_dwordx4 v[56:59], v[0:1], off offset:2048
	global_load_dwordx4 v[60:63], v[0:1], off offset:3072
	global_load_dwordx4 v[64:67], v[8:9], off
	global_load_dwordx4 v[68:71], v[8:9], off offset:16
	global_load_dwordx4 v[72:75], v[8:9], off offset:32
	global_load_dwordx4 v[76:79], v[8:9], off offset:48
	global_load_dwordx4 v[80:83], v[10:11], off
	global_load_dwordx4 v[84:87], v[10:11], off offset:1024
	global_load_dwordx4 v[88:91], v[10:11], off offset:2048
	global_load_dwordx4 v[92:95], v[10:11], off offset:3072
	v_lshl_add_u64 v[8:9], v[8:9], 0, s[98:99]
	v_lshl_add_u64 v[10:11], v[10:11], 0, s[100:101]
	global_load_dwordx4 v[96:99], v[8:9], off
	global_load_dwordx4 v[100:103], v[8:9], off offset:16
	global_load_dwordx4 v[104:107], v[8:9], off offset:32
	global_load_dwordx4 v[108:111], v[8:9], off offset:48
	global_load_dwordx4 v[112:115], v[10:11], off
	global_load_dwordx4 v[116:119], v[10:11], off offset:1024
	global_load_dwordx4 v[120:123], v[10:11], off offset:2048
	global_load_dwordx4 v[124:127], v[10:11], off offset:3072
	v_lshl_add_u64 v[8:9], v[8:9], 0, s[98:99]
	v_lshl_add_u64 v[10:11], v[10:11], 0, s[100:101]
	global_load_dwordx4 v[128:131], v[8:9], off
	global_load_dwordx4 v[132:135], v[8:9], off offset:16
	global_load_dwordx4 v[136:139], v[8:9], off offset:32
	global_load_dwordx4 v[140:143], v[8:9], off offset:48
	global_load_dwordx4 v[144:147], v[10:11], off
	global_load_dwordx4 v[148:151], v[10:11], off offset:1024
	global_load_dwordx4 v[152:155], v[10:11], off offset:2048
	global_load_dwordx4 v[156:159], v[10:11], off offset:3072
	v_lshl_add_u64 v[8:9], v[8:9], 0, s[98:99]
	v_lshl_add_u64 v[10:11], v[10:11], 0, s[100:101]
	global_load_dwordx4 v[160:163], v[8:9], off
	global_load_dwordx4 v[164:167], v[8:9], off offset:16
	global_load_dwordx4 v[168:171], v[8:9], off offset:32
	global_load_dwordx4 v[172:175], v[8:9], off offset:48
	global_load_dwordx4 v[176:179], v[10:11], off
	global_load_dwordx4 v[180:183], v[10:11], off offset:1024
	global_load_dwordx4 v[184:187], v[10:11], off offset:2048
	global_load_dwordx4 v[188:191], v[10:11], off offset:3072
	v_lshl_add_u64 v[8:9], v[8:9], 0, s[98:99]
	v_lshl_add_u64 v[10:11], v[10:11], 0, s[100:101]
	s_waitcnt vmcnt(24)
	v_add_f32_e32 v14, v64, v65
	v_add_f32_e32 v5, v66, v67
	v_add_f32_e32 v14, v14, v5
	v_add_f32_e32 v15, v68, v69
	v_add_f32_e32 v5, v70, v71
	v_add_f32_e32 v15, v15, v5
	v_add_f32_e32 v16, v72, v73
	v_add_f32_e32 v5, v74, v75
	v_add_f32_e32 v16, v16, v5
	v_add_f32_e32 v17, v76, v77
	v_add_f32_e32 v5, v78, v79
	v_add_f32_e32 v17, v17, v5
	v_add_f32_e32 v5, v14, v15
	v_add_f32_e32 v5, v5, v16
	v_add_f32_e32 v5, v5, v17
	v_fmamk_f32 v5, v5, 0x3a800000, v6
	v_mul_f32_e32 v7, 0x4b800000, v5
	v_cmp_gt_f32_e32 vcc, s3, v5
	s_nop 1
	v_cndmask_b32_e32 v5, v5, v7, vcc
	v_rsq_f32_e32 v5, v5
	s_nop 0
	v_mul_f32_e32 v7, 0x45800000, v5
	v_cndmask_b32_e32 v20, v5, v7, vcc
	v_pk_mul_f32 v[24:25], v[80:81], v[20:21] op_sel_hi:[1,0]
	v_pk_mul_f32 v[26:27], v[82:83], v[20:21] op_sel_hi:[1,0]
	v_pk_mul_f32 v[24:25], v[48:49], v[24:25]
	v_pk_mul_f32 v[26:27], v[50:51], v[26:27]
	global_store_dwordx4 v[12:13], v[24:27], off
	v_pk_mul_f32 v[28:29], v[84:85], v[20:21] op_sel_hi:[1,0]
	v_pk_mul_f32 v[30:31], v[86:87], v[20:21] op_sel_hi:[1,0]
	v_pk_mul_f32 v[28:29], v[52:53], v[28:29]
	v_pk_mul_f32 v[30:31], v[54:55], v[30:31]
	global_store_dwordx4 v[12:13], v[28:31], off offset:1024
	v_pk_mul_f32 v[32:33], v[88:89], v[20:21] op_sel_hi:[1,0]
	v_pk_mul_f32 v[34:35], v[90:91], v[20:21] op_sel_hi:[1,0]
	v_pk_mul_f32 v[32:33], v[56:57], v[32:33]
	v_pk_mul_f32 v[34:35], v[58:59], v[34:35]
	global_store_dwordx4 v[12:13], v[32:35], off offset:2048
	v_pk_mul_f32 v[36:37], v[92:93], v[20:21] op_sel_hi:[1,0]
	v_pk_mul_f32 v[38:39], v[94:95], v[20:21] op_sel_hi:[1,0]
	v_pk_mul_f32 v[36:37], v[60:61], v[36:37]
	v_pk_mul_f32 v[38:39], v[62:63], v[38:39]
	global_store_dwordx4 v[12:13], v[36:39], off offset:3072
	v_lshl_add_u64 v[12:13], v[12:13], 0, s[100:101]
	global_load_dwordx4 v[64:67], v[8:9], off
	global_load_dwordx4 v[68:71], v[8:9], off offset:16
	global_load_dwordx4 v[72:75], v[8:9], off offset:32
	global_load_dwordx4 v[76:79], v[8:9], off offset:48
	global_load_dwordx4 v[80:83], v[10:11], off
	global_load_dwordx4 v[84:87], v[10:11], off offset:1024
	global_load_dwordx4 v[88:91], v[10:11], off offset:2048
	global_load_dwordx4 v[92:95], v[10:11], off offset:3072
	v_lshl_add_u64 v[8:9], v[8:9], 0, s[98:99]
	v_lshl_add_u64 v[10:11], v[10:11], 0, s[100:101]
	s_waitcnt vmcnt(24)
; DI float rstd_from16(const float* p, float inv_n) {
;   const f32x4 a = *(const f32x4*)p, b = *(const f32x4*)(p + 4), c = *(const f32x4*)(p + 8), d = *(const f32x4*)(p + 12);
;   const float s = ((a[0] + a[1]) + (a[2] + a[3])) + ((b[0] + b[1]) + (b[2] + b[3])) + ((c[0] + c[1]) + (c[2] + c[3])) + ((d[0] + d[1]) + (d[2] + d[3]));
;   return rsqrtf(s * inv_n + EPS_);
; DI void phase_final(const Params& p) {
;     ...
;   for (int it = blockIdx.x; it < T_ / 8; it += gridDim.x) {
;     const int t = it * 8 + wid; const float rs = rstd_from16((const float*)(p.ws + O_SSQ) + (size_t)t * 16, 1.f / 1024.f);
;     float* xr = p.out + (size_t)t * D_;
; #pragma unroll
;     for (int c = 0; c < 4; ++c) { const int k = c * 256 + lane * 4; const f32x4 v = *(const f32x4*)(xr + k), gv = *(const f32x4*)(p.final_norm + k); *(f32x4*)(xr + k) = v * rs * gv; }
;   }
	v_add_f32_e32 v14, v96, v97
	v_add_f32_e32 v5, v98, v99
	v_add_f32_e32 v14, v14, v5
	v_add_f32_e32 v15, v100, v101
	v_add_f32_e32 v5, v102, v103
	v_add_f32_e32 v15, v15, v5
	v_add_f32_e32 v16, v104, v105
	v_add_f32_e32 v5, v106, v107
	v_add_f32_e32 v16, v16, v5
	v_add_f32_e32 v17, v108, v109
	v_add_f32_e32 v5, v110, v111
	v_add_f32_e32 v17, v17, v5
	v_add_f32_e32 v5, v14, v15
	v_add_f32_e32 v5, v5, v16
	v_add_f32_e32 v5, v5, v17
	v_fmamk_f32 v5, v5, 0x3a800000, v6
	v_mul_f32_e32 v7, 0x4b800000, v5
	v_cmp_gt_f32_e32 vcc, s3, v5
	s_nop 1
	v_cndmask_b32_e32 v5, v5, v7, vcc
	v_rsq_f32_e32 v5, v5
	s_nop 0
	v_mul_f32_e32 v7, 0x45800000, v5
	v_cndmask_b32_e32 v20, v5, v7, vcc
	v_pk_mul_f32 v[192:193], v[112:113], v[20:21] op_sel_hi:[1,0]
	v_pk_mul_f32 v[194:195], v[114:115], v[20:21] op_sel_hi:[1,0]
	v_pk_mul_f32 v[192:193], v[48:49], v[192:193]
	v_pk_mul_f32 v[194:195], v[50:51], v[194:195]
	global_store_dwordx4 v[12:13], v[192:195], off
	v_pk_mul_f32 v[196:197], v[116:117], v[20:21] op_sel_hi:[1,0]
	v_pk_mul_f32 v[198:199], v[118:119], v[20:21] op_sel_hi:[1,0]
	v_pk_mul_f32 v[196:197], v[52:53], v[196:197]
	v_pk_mul_f32 v[198:199], v[54:55], v[198:199]
	global_store_dwordx4 v[12:13], v[196:199], off offset:1024
	v_pk_mul_f32 v[200:201], v[120:121], v[20:21] op_sel_hi:[1,0]
	v_pk_mul_f32 v[202:203], v[122:123], v[20:21] op_sel_hi:[1,0]
	v_pk_mul_f32 v[200:201], v[56:57], v[200:201]
	v_pk_mul_f32 v[202:203], v[58:59], v[202:203]
	global_store_dwordx4 v[12:13], v[200:203], off offset:2048
	v_pk_mul_f32 v[204:205], v[124:125], v[20:21] op_sel_hi:[1,0]
	v_pk_mul_f32 v[206:207], v[126:127], v[20:21] op_sel_hi:[1,0]
	v_pk_mul_f32 v[204:205], v[60:61], v[204:205]
	v_pk_mul_f32 v[206:207], v[62:63], v[206:207]
	global_store_dwordx4 v[12:13], v[204:207], off offset:3072
	v_lshl_add_u64 v[12:13], v[12:13], 0, s[100:101]
	global_load_dwordx4 v[96:99], v[8:9], off
	global_load_dwordx4 v[100:103], v[8:9], off offset:16
	global_load_dwordx4 v[104:107], v[8:9], off offset:32
	global_load_dwordx4 v[108:111], v[8:9], off offset:48
	global_load_dwordx4 v[112:115], v[10:11], off
	global_load_dwordx4 v[116:119], v[10:11], off offset:1024
	global_load_dwordx4 v[120:123], v[10:11], off offset:2048
	global_load_dwordx4 v[124:127], v[10:11], off offset:3072
	v_lshl_add_u64 v[8:9], v[8:9], 0, s[98:99]
	v_lshl_add_u64 v[10:11], v[10:11], 0, s[100:101]
	s_waitcnt vmcnt(24)
	v_add_f32_e32 v14, v128, v129
	v_add_f32_e32 v5, v130, v131
	v_add_f32_e32 v14, v14, v5
	v_add_f32_e32 v15, v132, v133
	v_add_f32_e32 v5, v134, v135
	v_add_f32_e32 v15, v15, v5
	v_add_f32_e32 v16, v136, v137
	v_add_f32_e32 v5, v138, v139
	v_add_f32_e32 v16, v16, v5
	v_add_f32_e32 v17, v140, v141
	v_add_f32_e32 v5, v142, v143
	v_add_f32_e32 v17, v17, v5
	v_add_f32_e32 v5, v14, v15
	v_add_f32_e32 v5, v5, v16
	v_add_f32_e32 v5, v5, v17
	v_fmamk_f32 v5, v5, 0x3a800000, v6
	v_mul_f32_e32 v7, 0x4b800000, v5
	v_cmp_gt_f32_e32 vcc, s3, v5
	s_nop 1
	v_cndmask_b32_e32 v5, v5, v7, vcc
	v_rsq_f32_e32 v5, v5
	s_nop 0
	v_mul_f32_e32 v7, 0x45800000, v5
	v_cndmask_b32_e32 v20, v5, v7, vcc
	v_pk_mul_f32 v[24:25], v[144:145], v[20:21] op_sel_hi:[1,0]
	v_pk_mul_f32 v[26:27], v[146:147], v[20:21] op_sel_hi:[1,0]
	v_pk_mul_f32 v[24:25], v[48:49], v[24:25]
	v_pk_mul_f32 v[26:27], v[50:51], v[26:27]
	global_store_dwordx4 v[12:13], v[24:27], off
	v_pk_mul_f32 v[28:29], v[148:149], v[20:21] op_sel_hi:[1,0]
	v_pk_mul_f32 v[30:31], v[150:151], v[20:21] op_sel_hi:[1,0]
	v_pk_mul_f32 v[28:29], v[52:53], v[28:29]
	v_pk_mul_f32 v[30:31], v[54:55], v[30:31]
	global_store_dwordx4 v[12:13], v[28:31], off offset:1024
	v_pk_mul_f32 v[32:33], v[152:153], v[20:21] op_sel_hi:[1,0]
	v_pk_mul_f32 v[34:35], v[154:155], v[20:21] op_sel_hi:[1,0]
	v_pk_mul_f32 v[32:33], v[56:57], v[32:33]
	v_pk_mul_f32 v[34:35], v[58:59], v[34:35]
	global_store_dwordx4 v[12:13], v[32:35], off offset:2048
	v_pk_mul_f32 v[36:37], v[156:157], v[20:21] op_sel_hi:[1,0]
	v_pk_mul_f32 v[38:39], v[158:159], v[20:21] op_sel_hi:[1,0]
	v_pk_mul_f32 v[36:37], v[60:61], v[36:37]
	v_pk_mul_f32 v[38:39], v[62:63], v[38:39]
	global_store_dwordx4 v[12:13], v[36:39], off offset:3072
	v_lshl_add_u64 v[12:13], v[12:13], 0, s[100:101]
	global_load_dwordx4 v[128:131], v[8:9], off
	global_load_dwordx4 v[132:135], v[8:9], off offset:16
	global_load_dwordx4 v[136:139], v[8:9], off offset:32
	global_load_dwordx4 v[140:143], v[8:9], off offset:48
	global_load_dwordx4 v[144:147], v[10:11], off
	global_load_dwordx4 v[148:151], v[10:11], off offset:1024
	global_load_dwordx4 v[152:155], v[10:11], off offset:2048
	global_load_dwordx4 v[156:159], v[10:11], off offset:3072
	v_lshl_add_u64 v[8:9], v[8:9], 0, s[98:99]
	v_lshl_add_u64 v[10:11], v[10:11], 0, s[100:101]
	s_waitcnt vmcnt(24)
; DI float rstd_from16(const float* p, float inv_n) {
;   const f32x4 a = *(const f32x4*)p, b = *(const f32x4*)(p + 4), c = *(const f32x4*)(p + 8), d = *(const f32x4*)(p + 12);
;   const float s = ((a[0] + a[1]) + (a[2] + a[3])) + ((b[0] + b[1]) + (b[2] + b[3])) + ((c[0] + c[1]) + (c[2] + c[3])) + ((d[0] + d[1]) + (d[2] + d[3]));
;   return rsqrtf(s * inv_n + EPS_);
; DI void phase_final(const Params& p) {
;     ...
;   for (int it = blockIdx.x; it < T_ / 8; it += gridDim.x) {
;     const int t = it * 8 + wid; const float rs = rstd_from16((const float*)(p.ws + O_SSQ) + (size_t)t * 16, 1.f / 1024.f);
;     float* xr = p.out + (size_t)t * D_;
; #pragma unroll
;     for (int c = 0; c < 4; ++c) { const int k = c * 256 + lane * 4; const f32x4 v = *(const f32x4*)(xr + k), gv = *(const f32x4*)(p.final_norm + k); *(f32x4*)(xr + k) = v * rs * gv; }
;   }
	v_add_f32_e32 v14, v160, v161
	v_add_f32_e32 v5, v162, v163
	v_add_f32_e32 v14, v14, v5
	v_add_f32_e32 v15, v164, v165
	v_add_f32_e32 v5, v166, v167
	v_add_f32_e32 v15, v15, v5
	v_add_f32_e32 v16, v168, v169
	v_add_f32_e32 v5, v170, v171
	v_add_f32_e32 v16, v16, v5
	v_add_f32_e32 v17, v172, v173
	v_add_f32_e32 v5, v174, v175
	v_add_f32_e32 v17, v17, v5
	v_add_f32_e32 v5, v14, v15
	v_add_f32_e32 v5, v5, v16
	v_add_f32_e32 v5, v5, v17
	v_fmamk_f32 v5, v5, 0x3a800000, v6
	v_mul_f32_e32 v7, 0x4b800000, v5
	v_cmp_gt_f32_e32 vcc, s3, v5
	s_nop 1
	v_cndmask_b32_e32 v5, v5, v7, vcc
	v_rsq_f32_e32 v5, v5
	s_nop 0
	v_mul_f32_e32 v7, 0x45800000, v5
	v_cndmask_b32_e32 v20, v5, v7, vcc
	v_pk_mul_f32 v[192:193], v[176:177], v[20:21] op_sel_hi:[1,0]
	v_pk_mul_f32 v[194:195], v[178:179], v[20:21] op_sel_hi:[1,0]
	v_pk_mul_f32 v[192:193], v[48:49], v[192:193]
	v_pk_mul_f32 v[194:195], v[50:51], v[194:195]
	global_store_dwordx4 v[12:13], v[192:195], off
	v_pk_mul_f32 v[196:197], v[180:181], v[20:21] op_sel_hi:[1,0]
	v_pk_mul_f32 v[198:199], v[182:183], v[20:21] op_sel_hi:[1,0]
	v_pk_mul_f32 v[196:197], v[52:53], v[196:197]
	v_pk_mul_f32 v[198:199], v[54:55], v[198:199]
	global_store_dwordx4 v[12:13], v[196:199], off offset:1024
	v_pk_mul_f32 v[200:201], v[184:185], v[20:21] op_sel_hi:[1,0]
	v_pk_mul_f32 v[202:203], v[186:187], v[20:21] op_sel_hi:[1,0]
	v_pk_mul_f32 v[200:201], v[56:57], v[200:201]
	v_pk_mul_f32 v[202:203], v[58:59], v[202:203]
	global_store_dwordx4 v[12:13], v[200:203], off offset:2048
	v_pk_mul_f32 v[204:205], v[188:189], v[20:21] op_sel_hi:[1,0]
	v_pk_mul_f32 v[206:207], v[190:191], v[20:21] op_sel_hi:[1,0]
	v_pk_mul_f32 v[204:205], v[60:61], v[204:205]
	v_pk_mul_f32 v[206:207], v[62:63], v[206:207]
	global_store_dwordx4 v[12:13], v[204:207], off offset:3072
	v_lshl_add_u64 v[12:13], v[12:13], 0, s[100:101]
	global_load_dwordx4 v[160:163], v[8:9], off
	global_load_dwordx4 v[164:167], v[8:9], off offset:16
	global_load_dwordx4 v[168:171], v[8:9], off offset:32
	global_load_dwordx4 v[172:175], v[8:9], off offset:48
	global_load_dwordx4 v[176:179], v[10:11], off
	global_load_dwordx4 v[180:183], v[10:11], off offset:1024
	global_load_dwordx4 v[184:187], v[10:11], off offset:2048
	global_load_dwordx4 v[188:191], v[10:11], off offset:3072
	v_lshl_add_u64 v[8:9], v[8:9], 0, s[98:99]
	v_lshl_add_u64 v[10:11], v[10:11], 0, s[100:101]
	s_waitcnt vmcnt(24)
	v_add_f32_e32 v14, v64, v65
	v_add_f32_e32 v5, v66, v67
	v_add_f32_e32 v14, v14, v5
	v_add_f32_e32 v15, v68, v69
	v_add_f32_e32 v5, v70, v71
	v_add_f32_e32 v15, v15, v5
	v_add_f32_e32 v16, v72, v73
	v_add_f32_e32 v5, v74, v75
	v_add_f32_e32 v16, v16, v5
	v_add_f32_e32 v17, v76, v77
	v_add_f32_e32 v5, v78, v79
	v_add_f32_e32 v17, v17, v5
	v_add_f32_e32 v5, v14, v15
	v_add_f32_e32 v5, v5, v16
	v_add_f32_e32 v5, v5, v17
	v_fmamk_f32 v5, v5, 0x3a800000, v6
	v_mul_f32_e32 v7, 0x4b800000, v5
	v_cmp_gt_f32_e32 vcc, s3, v5
	s_nop 1
	v_cndmask_b32_e32 v5, v5, v7, vcc
	v_rsq_f32_e32 v5, v5
	s_nop 0
	v_mul_f32_e32 v7, 0x45800000, v5
	v_cndmask_b32_e32 v20, v5, v7, vcc
	v_pk_mul_f32 v[24:25], v[80:81], v[20:21] op_sel_hi:[1,0]
	v_pk_mul_f32 v[26:27], v[82:83], v[20:21] op_sel_hi:[1,0]
	v_pk_mul_f32 v[24:25], v[48:49], v[24:25]
	v_pk_mul_f32 v[26:27], v[50:51], v[26:27]
	global_store_dwordx4 v[12:13], v[24:27], off
	v_pk_mul_f32 v[28:29], v[84:85], v[20:21] op_sel_hi:[1,0]
	v_pk_mul_f32 v[30:31], v[86:87], v[20:21] op_sel_hi:[1,0]
	v_pk_mul_f32 v[28:29], v[52:53], v[28:29]
	v_pk_mul_f32 v[30:31], v[54:55], v[30:31]
	global_store_dwordx4 v[12:13], v[28:31], off offset:1024
	v_pk_mul_f32 v[32:33], v[88:89], v[20:21] op_sel_hi:[1,0]
	v_pk_mul_f32 v[34:35], v[90:91], v[20:21] op_sel_hi:[1,0]
	v_pk_mul_f32 v[32:33], v[56:57], v[32:33]
	v_pk_mul_f32 v[34:35], v[58:59], v[34:35]
	global_store_dwordx4 v[12:13], v[32:35], off offset:2048
	v_pk_mul_f32 v[36:37], v[92:93], v[20:21] op_sel_hi:[1,0]
	v_pk_mul_f32 v[38:39], v[94:95], v[20:21] op_sel_hi:[1,0]
	v_pk_mul_f32 v[36:37], v[60:61], v[36:37]
	v_pk_mul_f32 v[38:39], v[62:63], v[38:39]
	global_store_dwordx4 v[12:13], v[36:39], off offset:3072
	v_lshl_add_u64 v[12:13], v[12:13], 0, s[100:101]
	global_load_dwordx4 v[64:67], v[8:9], off
	global_load_dwordx4 v[68:71], v[8:9], off offset:16
	global_load_dwordx4 v[72:75], v[8:9], off offset:32
	global_load_dwordx4 v[76:79], v[8:9], off offset:48
	global_load_dwordx4 v[80:83], v[10:11], off
	global_load_dwordx4 v[84:87], v[10:11], off offset:1024
	global_load_dwordx4 v[88:91], v[10:11], off offset:2048
	global_load_dwordx4 v[92:95], v[10:11], off offset:3072
	v_lshl_add_u64 v[8:9], v[8:9], 0, s[98:99]
	v_lshl_add_u64 v[10:11], v[10:11], 0, s[100:101]
	s_waitcnt vmcnt(24)
; DI float rstd_from16(const float* p, float inv_n) {
;   const f32x4 a = *(const f32x4*)p, b = *(const f32x4*)(p + 4), c = *(const f32x4*)(p + 8), d = *(const f32x4*)(p + 12);
;   const float s = ((a[0] + a[1]) + (a[2] + a[3])) + ((b[0] + b[1]) + (b[2] + b[3])) + ((c[0] + c[1]) + (c[2] + c[3])) + ((d[0] + d[1]) + (d[2] + d[3]));
;   return rsqrtf(s * inv_n + EPS_);
; DI void phase_final(const Params& p) {
;     ...
;   for (int it = blockIdx.x; it < T_ / 8; it += gridDim.x) {
;     const int t = it * 8 + wid; const float rs = rstd_from16((const float*)(p.ws + O_SSQ) + (size_t)t * 16, 1.f / 1024.f);
;     float* xr = p.out + (size_t)t * D_;
; #pragma unroll
;     for (int c = 0; c < 4; ++c) { const int k = c * 256 + lane * 4; const f32x4 v = *(const f32x4*)(xr + k), gv = *(const f32x4*)(p.final_norm + k); *(f32x4*)(xr + k) = v * rs * gv; }
;   }
	v_add_f32_e32 v14, v96, v97
	v_add_f32_e32 v5, v98, v99
	v_add_f32_e32 v14, v14, v5
	v_add_f32_e32 v15, v100, v101
	v_add_f32_e32 v5, v102, v103
	v_add_f32_e32 v15, v15, v5
	v_add_f32_e32 v16, v104, v105
	v_add_f32_e32 v5, v106, v107
	v_add_f32_e32 v16, v16, v5
	v_add_f32_e32 v17, v108, v109
	v_add_f32_e32 v5, v110, v111
	v_add_f32_e32 v17, v17, v5
	v_add_f32_e32 v5, v14, v15
	v_add_f32_e32 v5, v5, v16
	v_add_f32_e32 v5, v5, v17
	v_fmamk_f32 v5, v5, 0x3a800000, v6
	v_mul_f32_e32 v7, 0x4b800000, v5
	v_cmp_gt_f32_e32 vcc, s3, v5
	s_nop 1
	v_cndmask_b32_e32 v5, v5, v7, vcc
	v_rsq_f32_e32 v5, v5
	s_nop 0
	v_mul_f32_e32 v7, 0x45800000, v5
	v_cndmask_b32_e32 v20, v5, v7, vcc
	v_pk_mul_f32 v[192:193], v[112:113], v[20:21] op_sel_hi:[1,0]
	v_pk_mul_f32 v[194:195], v[114:115], v[20:21] op_sel_hi:[1,0]
	v_pk_mul_f32 v[192:193], v[48:49], v[192:193]
	v_pk_mul_f32 v[194:195], v[50:51], v[194:195]
	global_store_dwordx4 v[12:13], v[192:195], off
	v_pk_mul_f32 v[196:197], v[116:117], v[20:21] op_sel_hi:[1,0]
	v_pk_mul_f32 v[198:199], v[118:119], v[20:21] op_sel_hi:[1,0]
	v_pk_mul_f32 v[196:197], v[52:53], v[196:197]
	v_pk_mul_f32 v[198:199], v[54:55], v[198:199]
	global_store_dwordx4 v[12:13], v[196:199], off offset:1024
	v_pk_mul_f32 v[200:201], v[120:121], v[20:21] op_sel_hi:[1,0]
	v_pk_mul_f32 v[202:203], v[122:123], v[20:21] op_sel_hi:[1,0]
	v_pk_mul_f32 v[200:201], v[56:57], v[200:201]
	v_pk_mul_f32 v[202:203], v[58:59], v[202:203]
	global_store_dwordx4 v[12:13], v[200:203], off offset:2048
	v_pk_mul_f32 v[204:205], v[124:125], v[20:21] op_sel_hi:[1,0]
	v_pk_mul_f32 v[206:207], v[126:127], v[20:21] op_sel_hi:[1,0]
	v_pk_mul_f32 v[204:205], v[60:61], v[204:205]
	v_pk_mul_f32 v[206:207], v[62:63], v[206:207]
	global_store_dwordx4 v[12:13], v[204:207], off offset:3072
	v_lshl_add_u64 v[12:13], v[12:13], 0, s[100:101]
	global_load_dwordx4 v[96:99], v[8:9], off
	global_load_dwordx4 v[100:103], v[8:9], off offset:16
	global_load_dwordx4 v[104:107], v[8:9], off offset:32
	global_load_dwordx4 v[108:111], v[8:9], off offset:48
	global_load_dwordx4 v[112:115], v[10:11], off
	global_load_dwordx4 v[116:119], v[10:11], off offset:1024
	global_load_dwordx4 v[120:123], v[10:11], off offset:2048
	global_load_dwordx4 v[124:127], v[10:11], off offset:3072
	v_lshl_add_u64 v[8:9], v[8:9], 0, s[98:99]
	v_lshl_add_u64 v[10:11], v[10:11], 0, s[100:101]
	s_waitcnt vmcnt(24)
	v_add_f32_e32 v14, v128, v129
	v_add_f32_e32 v5, v130, v131
	v_add_f32_e32 v14, v14, v5
	v_add_f32_e32 v15, v132, v133
	v_add_f32_e32 v5, v134, v135
	v_add_f32_e32 v15, v15, v5
	v_add_f32_e32 v16, v136, v137
	v_add_f32_e32 v5, v138, v139
	v_add_f32_e32 v16, v16, v5
	v_add_f32_e32 v17, v140, v141
	v_add_f32_e32 v5, v142, v143
	v_add_f32_e32 v17, v17, v5
	v_add_f32_e32 v5, v14, v15
	v_add_f32_e32 v5, v5, v16
	v_add_f32_e32 v5, v5, v17
	v_fmamk_f32 v5, v5, 0x3a800000, v6
	v_mul_f32_e32 v7, 0x4b800000, v5
	v_cmp_gt_f32_e32 vcc, s3, v5
	s_nop 1
	v_cndmask_b32_e32 v5, v5, v7, vcc
	v_rsq_f32_e32 v5, v5
	s_nop 0
	v_mul_f32_e32 v7, 0x45800000, v5
	v_cndmask_b32_e32 v20, v5, v7, vcc
	v_pk_mul_f32 v[24:25], v[144:145], v[20:21] op_sel_hi:[1,0]
	v_pk_mul_f32 v[26:27], v[146:147], v[20:21] op_sel_hi:[1,0]
	v_pk_mul_f32 v[24:25], v[48:49], v[24:25]
	v_pk_mul_f32 v[26:27], v[50:51], v[26:27]
	global_store_dwordx4 v[12:13], v[24:27], off
	v_pk_mul_f32 v[28:29], v[148:149], v[20:21] op_sel_hi:[1,0]
	v_pk_mul_f32 v[30:31], v[150:151], v[20:21] op_sel_hi:[1,0]
	v_pk_mul_f32 v[28:29], v[52:53], v[28:29]
	v_pk_mul_f32 v[30:31], v[54:55], v[30:31]
	global_store_dwordx4 v[12:13], v[28:31], off offset:1024
	v_pk_mul_f32 v[32:33], v[152:153], v[20:21] op_sel_hi:[1,0]
	v_pk_mul_f32 v[34:35], v[154:155], v[20:21] op_sel_hi:[1,0]
	v_pk_mul_f32 v[32:33], v[56:57], v[32:33]
	v_pk_mul_f32 v[34:35], v[58:59], v[34:35]
	global_store_dwordx4 v[12:13], v[32:35], off offset:2048
	v_pk_mul_f32 v[36:37], v[156:157], v[20:21] op_sel_hi:[1,0]
	v_pk_mul_f32 v[38:39], v[158:159], v[20:21] op_sel_hi:[1,0]
	v_pk_mul_f32 v[36:37], v[60:61], v[36:37]
	v_pk_mul_f32 v[38:39], v[62:63], v[38:39]
	global_store_dwordx4 v[12:13], v[36:39], off offset:3072
	v_lshl_add_u64 v[12:13], v[12:13], 0, s[100:101]
	global_load_dwordx4 v[128:131], v[8:9], off
	global_load_dwordx4 v[132:135], v[8:9], off offset:16
	global_load_dwordx4 v[136:139], v[8:9], off offset:32
	global_load_dwordx4 v[140:143], v[8:9], off offset:48
	global_load_dwordx4 v[144:147], v[10:11], off
	global_load_dwordx4 v[148:151], v[10:11], off offset:1024
	global_load_dwordx4 v[152:155], v[10:11], off offset:2048
	global_load_dwordx4 v[156:159], v[10:11], off offset:3072
	v_lshl_add_u64 v[8:9], v[8:9], 0, s[98:99]
	v_lshl_add_u64 v[10:11], v[10:11], 0, s[100:101]
	s_waitcnt vmcnt(24)
; DI float rstd_from16(const float* p, float inv_n) {
;   const f32x4 a = *(const f32x4*)p, b = *(const f32x4*)(p + 4), c = *(const f32x4*)(p + 8), d = *(const f32x4*)(p + 12);
;   const float s = ((a[0] + a[1]) + (a[2] + a[3])) + ((b[0] + b[1]) + (b[2] + b[3])) + ((c[0] + c[1]) + (c[2] + c[3])) + ((d[0] + d[1]) + (d[2] + d[3]));
;   return rsqrtf(s * inv_n + EPS_);
; DI void phase_final(const Params& p) {
;     ...
;   for (int it = blockIdx.x; it < T_ / 8; it += gridDim.x) {
;     const int t = it * 8 + wid; const float rs = rstd_from16((const float*)(p.ws + O_SSQ) + (size_t)t * 16, 1.f / 1024.f);
;     float* xr = p.out + (size_t)t * D_;
; #pragma unroll
;     for (int c = 0; c < 4; ++c) { const int k = c * 256 + lane * 4; const f32x4 v = *(const f32x4*)(xr + k), gv = *(const f32x4*)(p.final_norm + k); *(f32x4*)(xr + k) = v * rs * gv; }
;   }
	v_add_f32_e32 v14, v160, v161
	v_add_f32_e32 v5, v162, v163
	v_add_f32_e32 v14, v14, v5
	v_add_f32_e32 v15, v164, v165
	v_add_f32_e32 v5, v166, v167
	v_add_f32_e32 v15, v15, v5
	v_add_f32_e32 v16, v168, v169
	v_add_f32_e32 v5, v170, v171
	v_add_f32_e32 v16, v16, v5
	v_add_f32_e32 v17, v172, v173
	v_add_f32_e32 v5, v174, v175
	v_add_f32_e32 v17, v17, v5
	v_add_f32_e32 v5, v14, v15
	v_add_f32_e32 v5, v5, v16
	v_add_f32_e32 v5, v5, v17
	v_fmamk_f32 v5, v5, 0x3a800000, v6
	v_mul_f32_e32 v7, 0x4b800000, v5
	v_cmp_gt_f32_e32 vcc, s3, v5
	s_nop 1
	v_cndmask_b32_e32 v5, v5, v7, vcc
	v_rsq_f32_e32 v5, v5
	s_nop 0
	v_mul_f32_e32 v7, 0x45800000, v5
	v_cndmask_b32_e32 v20, v5, v7, vcc
	v_pk_mul_f32 v[192:193], v[176:177], v[20:21] op_sel_hi:[1,0]
	v_pk_mul_f32 v[194:195], v[178:179], v[20:21] op_sel_hi:[1,0]
	v_pk_mul_f32 v[192:193], v[48:49], v[192:193]
	v_pk_mul_f32 v[194:195], v[50:51], v[194:195]
	global_store_dwordx4 v[12:13], v[192:195], off
	v_pk_mul_f32 v[196:197], v[180:181], v[20:21] op_sel_hi:[1,0]
	v_pk_mul_f32 v[198:199], v[182:183], v[20:21] op_sel_hi:[1,0]
	v_pk_mul_f32 v[196:197], v[52:53], v[196:197]
	v_pk_mul_f32 v[198:199], v[54:55], v[198:199]
	global_store_dwordx4 v[12:13], v[196:199], off offset:1024
	v_pk_mul_f32 v[200:201], v[184:185], v[20:21] op_sel_hi:[1,0]
	v_pk_mul_f32 v[202:203], v[186:187], v[20:21] op_sel_hi:[1,0]
	v_pk_mul_f32 v[200:201], v[56:57], v[200:201]
	v_pk_mul_f32 v[202:203], v[58:59], v[202:203]
	global_store_dwordx4 v[12:13], v[200:203], off offset:2048
	v_pk_mul_f32 v[204:205], v[188:189], v[20:21] op_sel_hi:[1,0]
	v_pk_mul_f32 v[206:207], v[190:191], v[20:21] op_sel_hi:[1,0]
	v_pk_mul_f32 v[204:205], v[60:61], v[204:205]
	v_pk_mul_f32 v[206:207], v[62:63], v[206:207]
	global_store_dwordx4 v[12:13], v[204:207], off offset:3072
	v_lshl_add_u64 v[12:13], v[12:13], 0, s[100:101]
	global_load_dwordx4 v[160:163], v[8:9], off
	global_load_dwordx4 v[164:167], v[8:9], off offset:16
	global_load_dwordx4 v[168:171], v[8:9], off offset:32
	global_load_dwordx4 v[172:175], v[8:9], off offset:48
	global_load_dwordx4 v[176:179], v[10:11], off
	global_load_dwordx4 v[180:183], v[10:11], off offset:1024
	global_load_dwordx4 v[184:187], v[10:11], off offset:2048
	global_load_dwordx4 v[188:191], v[10:11], off offset:3072
	v_lshl_add_u64 v[8:9], v[8:9], 0, s[98:99]
	v_lshl_add_u64 v[10:11], v[10:11], 0, s[100:101]
	s_waitcnt vmcnt(24)
	v_add_f32_e32 v14, v64, v65
	v_add_f32_e32 v5, v66, v67
	v_add_f32_e32 v14, v14, v5
	v_add_f32_e32 v15, v68, v69
	v_add_f32_e32 v5, v70, v71
	v_add_f32_e32 v15, v15, v5
	v_add_f32_e32 v16, v72, v73
	v_add_f32_e32 v5, v74, v75
	v_add_f32_e32 v16, v16, v5
	v_add_f32_e32 v17, v76, v77
	v_add_f32_e32 v5, v78, v79
	v_add_f32_e32 v17, v17, v5
	v_add_f32_e32 v5, v14, v15
	v_add_f32_e32 v5, v5, v16
	v_add_f32_e32 v5, v5, v17
	v_fmamk_f32 v5, v5, 0x3a800000, v6
	v_mul_f32_e32 v7, 0x4b800000, v5
	v_cmp_gt_f32_e32 vcc, s3, v5
	s_nop 1
	v_cndmask_b32_e32 v5, v5, v7, vcc
	v_rsq_f32_e32 v5, v5
	s_nop 0
	v_mul_f32_e32 v7, 0x45800000, v5
	v_cndmask_b32_e32 v20, v5, v7, vcc
	v_pk_mul_f32 v[24:25], v[80:81], v[20:21] op_sel_hi:[1,0]
	v_pk_mul_f32 v[26:27], v[82:83], v[20:21] op_sel_hi:[1,0]
	v_pk_mul_f32 v[24:25], v[48:49], v[24:25]
	v_pk_mul_f32 v[26:27], v[50:51], v[26:27]
	global_store_dwordx4 v[12:13], v[24:27], off
	v_pk_mul_f32 v[28:29], v[84:85], v[20:21] op_sel_hi:[1,0]
	v_pk_mul_f32 v[30:31], v[86:87], v[20:21] op_sel_hi:[1,0]
	v_pk_mul_f32 v[28:29], v[52:53], v[28:29]
	v_pk_mul_f32 v[30:31], v[54:55], v[30:31]
	global_store_dwordx4 v[12:13], v[28:31], off offset:1024
	v_pk_mul_f32 v[32:33], v[88:89], v[20:21] op_sel_hi:[1,0]
	v_pk_mul_f32 v[34:35], v[90:91], v[20:21] op_sel_hi:[1,0]
	v_pk_mul_f32 v[32:33], v[56:57], v[32:33]
	v_pk_mul_f32 v[34:35], v[58:59], v[34:35]
	global_store_dwordx4 v[12:13], v[32:35], off offset:2048
	v_pk_mul_f32 v[36:37], v[92:93], v[20:21] op_sel_hi:[1,0]
	v_pk_mul_f32 v[38:39], v[94:95], v[20:21] op_sel_hi:[1,0]
	v_pk_mul_f32 v[36:37], v[60:61], v[36:37]
	v_pk_mul_f32 v[38:39], v[62:63], v[38:39]
	global_store_dwordx4 v[12:13], v[36:39], off offset:3072
	v_lshl_add_u64 v[12:13], v[12:13], 0, s[100:101]
	global_load_dwordx4 v[64:67], v[8:9], off
	global_load_dwordx4 v[68:71], v[8:9], off offset:16
	global_load_dwordx4 v[72:75], v[8:9], off offset:32
	global_load_dwordx4 v[76:79], v[8:9], off offset:48
	global_load_dwordx4 v[80:83], v[10:11], off
	global_load_dwordx4 v[84:87], v[10:11], off offset:1024
	global_load_dwordx4 v[88:91], v[10:11], off offset:2048
	global_load_dwordx4 v[92:95], v[10:11], off offset:3072
	v_lshl_add_u64 v[8:9], v[8:9], 0, s[98:99]
	v_lshl_add_u64 v[10:11], v[10:11], 0, s[100:101]
	s_waitcnt vmcnt(24)
; DI float rstd_from16(const float* p, float inv_n) {
;   const f32x4 a = *(const f32x4*)p, b = *(const f32x4*)(p + 4), c = *(const f32x4*)(p + 8), d = *(const f32x4*)(p + 12);
;   const float s = ((a[0] + a[1]) + (a[2] + a[3])) + ((b[0] + b[1]) + (b[2] + b[3])) + ((c[0] + c[1]) + (c[2] + c[3])) + ((d[0] + d[1]) + (d[2] + d[3]));
;   return rsqrtf(s * inv_n + EPS_);
; DI void phase_final(const Params& p) {
;     ...
;   for (int it = blockIdx.x; it < T_ / 8; it += gridDim.x) {
;     const int t = it * 8 + wid; const float rs = rstd_from16((const float*)(p.ws + O_SSQ) + (size_t)t * 16, 1.f / 1024.f);
;     float* xr = p.out + (size_t)t * D_;
; #pragma unroll
;     for (int c = 0; c < 4; ++c) { const int k = c * 256 + lane * 4; const f32x4 v = *(const f32x4*)(xr + k), gv = *(const f32x4*)(p.final_norm + k); *(f32x4*)(xr + k) = v * rs * gv; }
;   }
	v_add_f32_e32 v14, v96, v97
	v_add_f32_e32 v5, v98, v99
	v_add_f32_e32 v14, v14, v5
	v_add_f32_e32 v15, v100, v101
	v_add_f32_e32 v5, v102, v103
	v_add_f32_e32 v15, v15, v5
	v_add_f32_e32 v16, v104, v105
	v_add_f32_e32 v5, v106, v107
	v_add_f32_e32 v16, v16, v5
	v_add_f32_e32 v17, v108, v109
	v_add_f32_e32 v5, v110, v111
	v_add_f32_e32 v17, v17, v5
	v_add_f32_e32 v5, v14, v15
	v_add_f32_e32 v5, v5, v16
	v_add_f32_e32 v5, v5, v17
	v_fmamk_f32 v5, v5, 0x3a800000, v6
	v_mul_f32_e32 v7, 0x4b800000, v5
	v_cmp_gt_f32_e32 vcc, s3, v5
	s_nop 1
	v_cndmask_b32_e32 v5, v5, v7, vcc
	v_rsq_f32_e32 v5, v5
	s_nop 0
	v_mul_f32_e32 v7, 0x45800000, v5
	v_cndmask_b32_e32 v20, v5, v7, vcc
	v_pk_mul_f32 v[192:193], v[112:113], v[20:21] op_sel_hi:[1,0]
	v_pk_mul_f32 v[194:195], v[114:115], v[20:21] op_sel_hi:[1,0]
	v_pk_mul_f32 v[192:193], v[48:49], v[192:193]
	v_pk_mul_f32 v[194:195], v[50:51], v[194:195]
	global_store_dwordx4 v[12:13], v[192:195], off
	v_pk_mul_f32 v[196:197], v[116:117], v[20:21] op_sel_hi:[1,0]
	v_pk_mul_f32 v[198:199], v[118:119], v[20:21] op_sel_hi:[1,0]
	v_pk_mul_f32 v[196:197], v[52:53], v[196:197]
	v_pk_mul_f32 v[198:199], v[54:55], v[198:199]
	global_store_dwordx4 v[12:13], v[196:199], off offset:1024
	v_pk_mul_f32 v[200:201], v[120:121], v[20:21] op_sel_hi:[1,0]
	v_pk_mul_f32 v[202:203], v[122:123], v[20:21] op_sel_hi:[1,0]
	v_pk_mul_f32 v[200:201], v[56:57], v[200:201]
	v_pk_mul_f32 v[202:203], v[58:59], v[202:203]
	global_store_dwordx4 v[12:13], v[200:203], off offset:2048
	v_pk_mul_f32 v[204:205], v[124:125], v[20:21] op_sel_hi:[1,0]
	v_pk_mul_f32 v[206:207], v[126:127], v[20:21] op_sel_hi:[1,0]
	v_pk_mul_f32 v[204:205], v[60:61], v[204:205]
	v_pk_mul_f32 v[206:207], v[62:63], v[206:207]
	global_store_dwordx4 v[12:13], v[204:207], off offset:3072
	v_lshl_add_u64 v[12:13], v[12:13], 0, s[100:101]
	global_load_dwordx4 v[96:99], v[8:9], off
	global_load_dwordx4 v[100:103], v[8:9], off offset:16
	global_load_dwordx4 v[104:107], v[8:9], off offset:32
	global_load_dwordx4 v[108:111], v[8:9], off offset:48
	global_load_dwordx4 v[112:115], v[10:11], off
	global_load_dwordx4 v[116:119], v[10:11], off offset:1024
	global_load_dwordx4 v[120:123], v[10:11], off offset:2048
	global_load_dwordx4 v[124:127], v[10:11], off offset:3072
	v_lshl_add_u64 v[8:9], v[8:9], 0, s[98:99]
	v_lshl_add_u64 v[10:11], v[10:11], 0, s[100:101]
	s_waitcnt vmcnt(24)
	v_add_f32_e32 v14, v128, v129
	v_add_f32_e32 v5, v130, v131
	v_add_f32_e32 v14, v14, v5
	v_add_f32_e32 v15, v132, v133
	v_add_f32_e32 v5, v134, v135
	v_add_f32_e32 v15, v15, v5
	v_add_f32_e32 v16, v136, v137
	v_add_f32_e32 v5, v138, v139
	v_add_f32_e32 v16, v16, v5
	v_add_f32_e32 v17, v140, v141
	v_add_f32_e32 v5, v142, v143
	v_add_f32_e32 v17, v17, v5
	v_add_f32_e32 v5, v14, v15
	v_add_f32_e32 v5, v5, v16
	v_add_f32_e32 v5, v5, v17
	v_fmamk_f32 v5, v5, 0x3a800000, v6
	v_mul_f32_e32 v7, 0x4b800000, v5
	v_cmp_gt_f32_e32 vcc, s3, v5
	s_nop 1
	v_cndmask_b32_e32 v5, v5, v7, vcc
	v_rsq_f32_e32 v5, v5
	s_nop 0
	v_mul_f32_e32 v7, 0x45800000, v5
	v_cndmask_b32_e32 v20, v5, v7, vcc
	v_pk_mul_f32 v[24:25], v[144:145], v[20:21] op_sel_hi:[1,0]
	v_pk_mul_f32 v[26:27], v[146:147], v[20:21] op_sel_hi:[1,0]
	v_pk_mul_f32 v[24:25], v[48:49], v[24:25]
	v_pk_mul_f32 v[26:27], v[50:51], v[26:27]
	global_store_dwordx4 v[12:13], v[24:27], off
	v_pk_mul_f32 v[28:29], v[148:149], v[20:21] op_sel_hi:[1,0]
	v_pk_mul_f32 v[30:31], v[150:151], v[20:21] op_sel_hi:[1,0]
	v_pk_mul_f32 v[28:29], v[52:53], v[28:29]
	v_pk_mul_f32 v[30:31], v[54:55], v[30:31]
	global_store_dwordx4 v[12:13], v[28:31], off offset:1024
	v_pk_mul_f32 v[32:33], v[152:153], v[20:21] op_sel_hi:[1,0]
	v_pk_mul_f32 v[34:35], v[154:155], v[20:21] op_sel_hi:[1,0]
	v_pk_mul_f32 v[32:33], v[56:57], v[32:33]
	v_pk_mul_f32 v[34:35], v[58:59], v[34:35]
	global_store_dwordx4 v[12:13], v[32:35], off offset:2048
	v_pk_mul_f32 v[36:37], v[156:157], v[20:21] op_sel_hi:[1,0]
	v_pk_mul_f32 v[38:39], v[158:159], v[20:21] op_sel_hi:[1,0]
	v_pk_mul_f32 v[36:37], v[60:61], v[36:37]
	v_pk_mul_f32 v[38:39], v[62:63], v[38:39]
	global_store_dwordx4 v[12:13], v[36:39], off offset:3072
	v_lshl_add_u64 v[12:13], v[12:13], 0, s[100:101]
	global_load_dwordx4 v[128:131], v[8:9], off
	global_load_dwordx4 v[132:135], v[8:9], off offset:16
	global_load_dwordx4 v[136:139], v[8:9], off offset:32
	global_load_dwordx4 v[140:143], v[8:9], off offset:48
	global_load_dwordx4 v[144:147], v[10:11], off
	global_load_dwordx4 v[148:151], v[10:11], off offset:1024
	global_load_dwordx4 v[152:155], v[10:11], off offset:2048
	global_load_dwordx4 v[156:159], v[10:11], off offset:3072
	v_lshl_add_u64 v[8:9], v[8:9], 0, s[98:99]
	v_lshl_add_u64 v[10:11], v[10:11], 0, s[100:101]
	s_waitcnt vmcnt(24)
; DI float rstd_from16(const float* p, float inv_n) {
;   const f32x4 a = *(const f32x4*)p, b = *(const f32x4*)(p + 4), c = *(const f32x4*)(p + 8), d = *(const f32x4*)(p + 12);
;   const float s = ((a[0] + a[1]) + (a[2] + a[3])) + ((b[0] + b[1]) + (b[2] + b[3])) + ((c[0] + c[1]) + (c[2] + c[3])) + ((d[0] + d[1]) + (d[2] + d[3]));
;   return rsqrtf(s * inv_n + EPS_);
; DI void phase_final(const Params& p) {
;     ...
;   for (int it = blockIdx.x; it < T_ / 8; it += gridDim.x) {
;     const int t = it * 8 + wid; const float rs = rstd_from16((const float*)(p.ws + O_SSQ) + (size_t)t * 16, 1.f / 1024.f);
;     float* xr = p.out + (size_t)t * D_;
; #pragma unroll
;     for (int c = 0; c < 4; ++c) { const int k = c * 256 + lane * 4; const f32x4 v = *(const f32x4*)(xr + k), gv = *(const f32x4*)(p.final_norm + k); *(f32x4*)(xr + k) = v * rs * gv; }
;   }
	v_add_f32_e32 v14, v160, v161
	v_add_f32_e32 v5, v162, v163
	v_add_f32_e32 v14, v14, v5
	v_add_f32_e32 v15, v164, v165
	v_add_f32_e32 v5, v166, v167
	v_add_f32_e32 v15, v15, v5
	v_add_f32_e32 v16, v168, v169
	v_add_f32_e32 v5, v170, v171
	v_add_f32_e32 v16, v16, v5
	v_add_f32_e32 v17, v172, v173
	v_add_f32_e32 v5, v174, v175
	v_add_f32_e32 v17, v17, v5
	v_add_f32_e32 v5, v14, v15
	v_add_f32_e32 v5, v5, v16
	v_add_f32_e32 v5, v5, v17
	v_fmamk_f32 v5, v5, 0x3a800000, v6
	v_mul_f32_e32 v7, 0x4b800000, v5
	v_cmp_gt_f32_e32 vcc, s3, v5
	s_nop 1
	v_cndmask_b32_e32 v5, v5, v7, vcc
	v_rsq_f32_e32 v5, v5
	s_nop 0
	v_mul_f32_e32 v7, 0x45800000, v5
	v_cndmask_b32_e32 v20, v5, v7, vcc
	v_pk_mul_f32 v[192:193], v[176:177], v[20:21] op_sel_hi:[1,0]
	v_pk_mul_f32 v[194:195], v[178:179], v[20:21] op_sel_hi:[1,0]
	v_pk_mul_f32 v[192:193], v[48:49], v[192:193]
	v_pk_mul_f32 v[194:195], v[50:51], v[194:195]
	global_store_dwordx4 v[12:13], v[192:195], off
	v_pk_mul_f32 v[196:197], v[180:181], v[20:21] op_sel_hi:[1,0]
	v_pk_mul_f32 v[198:199], v[182:183], v[20:21] op_sel_hi:[1,0]
	v_pk_mul_f32 v[196:197], v[52:53], v[196:197]
	v_pk_mul_f32 v[198:199], v[54:55], v[198:199]
	global_store_dwordx4 v[12:13], v[196:199], off offset:1024
	v_pk_mul_f32 v[200:201], v[184:185], v[20:21] op_sel_hi:[1,0]
	v_pk_mul_f32 v[202:203], v[186:187], v[20:21] op_sel_hi:[1,0]
	v_pk_mul_f32 v[200:201], v[56:57], v[200:201]
	v_pk_mul_f32 v[202:203], v[58:59], v[202:203]
	global_store_dwordx4 v[12:13], v[200:203], off offset:2048
	v_pk_mul_f32 v[204:205], v[188:189], v[20:21] op_sel_hi:[1,0]
	v_pk_mul_f32 v[206:207], v[190:191], v[20:21] op_sel_hi:[1,0]
	v_pk_mul_f32 v[204:205], v[60:61], v[204:205]
	v_pk_mul_f32 v[206:207], v[62:63], v[206:207]
	global_store_dwordx4 v[12:13], v[204:207], off offset:3072
	v_lshl_add_u64 v[12:13], v[12:13], 0, s[100:101]
	global_load_dwordx4 v[160:163], v[8:9], off
	global_load_dwordx4 v[164:167], v[8:9], off offset:16
	global_load_dwordx4 v[168:171], v[8:9], off offset:32
	global_load_dwordx4 v[172:175], v[8:9], off offset:48
	global_load_dwordx4 v[176:179], v[10:11], off
	global_load_dwordx4 v[180:183], v[10:11], off offset:1024
	global_load_dwordx4 v[184:187], v[10:11], off offset:2048
	global_load_dwordx4 v[188:191], v[10:11], off offset:3072
	v_lshl_add_u64 v[8:9], v[8:9], 0, s[98:99]
	v_lshl_add_u64 v[10:11], v[10:11], 0, s[100:101]
	s_waitcnt vmcnt(24)
	v_add_f32_e32 v14, v64, v65
	v_add_f32_e32 v5, v66, v67
	v_add_f32_e32 v14, v14, v5
	v_add_f32_e32 v15, v68, v69
	v_add_f32_e32 v5, v70, v71
	v_add_f32_e32 v15, v15, v5
	v_add_f32_e32 v16, v72, v73
	v_add_f32_e32 v5, v74, v75
	v_add_f32_e32 v16, v16, v5
	v_add_f32_e32 v17, v76, v77
	v_add_f32_e32 v5, v78, v79
	v_add_f32_e32 v17, v17, v5
	v_add_f32_e32 v5, v14, v15
	v_add_f32_e32 v5, v5, v16
	v_add_f32_e32 v5, v5, v17
	v_fmamk_f32 v5, v5, 0x3a800000, v6
	v_mul_f32_e32 v7, 0x4b800000, v5
	v_cmp_gt_f32_e32 vcc, s3, v5
	s_nop 1
	v_cndmask_b32_e32 v5, v5, v7, vcc
	v_rsq_f32_e32 v5, v5
	s_nop 0
	v_mul_f32_e32 v7, 0x45800000, v5
	v_cndmask_b32_e32 v20, v5, v7, vcc
	v_pk_mul_f32 v[24:25], v[80:81], v[20:21] op_sel_hi:[1,0]
	v_pk_mul_f32 v[26:27], v[82:83], v[20:21] op_sel_hi:[1,0]
	v_pk_mul_f32 v[24:25], v[48:49], v[24:25]
	v_pk_mul_f32 v[26:27], v[50:51], v[26:27]
	global_store_dwordx4 v[12:13], v[24:27], off
	v_pk_mul_f32 v[28:29], v[84:85], v[20:21] op_sel_hi:[1,0]
	v_pk_mul_f32 v[30:31], v[86:87], v[20:21] op_sel_hi:[1,0]
	v_pk_mul_f32 v[28:29], v[52:53], v[28:29]
	v_pk_mul_f32 v[30:31], v[54:55], v[30:31]
	global_store_dwordx4 v[12:13], v[28:31], off offset:1024
	v_pk_mul_f32 v[32:33], v[88:89], v[20:21] op_sel_hi:[1,0]
	v_pk_mul_f32 v[34:35], v[90:91], v[20:21] op_sel_hi:[1,0]
	v_pk_mul_f32 v[32:33], v[56:57], v[32:33]
	v_pk_mul_f32 v[34:35], v[58:59], v[34:35]
	global_store_dwordx4 v[12:13], v[32:35], off offset:2048
	v_pk_mul_f32 v[36:37], v[92:93], v[20:21] op_sel_hi:[1,0]
	v_pk_mul_f32 v[38:39], v[94:95], v[20:21] op_sel_hi:[1,0]
	v_pk_mul_f32 v[36:37], v[60:61], v[36:37]
	v_pk_mul_f32 v[38:39], v[62:63], v[38:39]
	global_store_dwordx4 v[12:13], v[36:39], off offset:3072
	v_lshl_add_u64 v[12:13], v[12:13], 0, s[100:101]
	s_waitcnt vmcnt(16)
; DI float rstd_from16(const float* p, float inv_n) {
;   const f32x4 a = *(const f32x4*)p, b = *(const f32x4*)(p + 4), c = *(const f32x4*)(p + 8), d = *(const f32x4*)(p + 12);
;   const float s = ((a[0] + a[1]) + (a[2] + a[3])) + ((b[0] + b[1]) + (b[2] + b[3])) + ((c[0] + c[1]) + (c[2] + c[3])) + ((d[0] + d[1]) + (d[2] + d[3]));
;   return rsqrtf(s * inv_n + EPS_);
; DI void phase_final(const Params& p) {
;     ...
;   for (int it = blockIdx.x; it < T_ / 8; it += gridDim.x) {
;     const int t = it * 8 + wid; const float rs = rstd_from16((const float*)(p.ws + O_SSQ) + (size_t)t * 16, 1.f / 1024.f);
;     float* xr = p.out + (size_t)t * D_;
; #pragma unroll
;     for (int c = 0; c < 4; ++c) { const int k = c * 256 + lane * 4; const f32x4 v = *(const f32x4*)(xr + k), gv = *(const f32x4*)(p.final_norm + k); *(f32x4*)(xr + k) = v * rs * gv; }
;   }
	v_add_f32_e32 v14, v96, v97
	v_add_f32_e32 v5, v98, v99
	v_add_f32_e32 v14, v14, v5
	v_add_f32_e32 v15, v100, v101
	v_add_f32_e32 v5, v102, v103
	v_add_f32_e32 v15, v15, v5
	v_add_f32_e32 v16, v104, v105
	v_add_f32_e32 v5, v106, v107
	v_add_f32_e32 v16, v16, v5
	v_add_f32_e32 v17, v108, v109
	v_add_f32_e32 v5, v110, v111
	v_add_f32_e32 v17, v17, v5
	v_add_f32_e32 v5, v14, v15
	v_add_f32_e32 v5, v5, v16
	v_add_f32_e32 v5, v5, v17
	v_fmamk_f32 v5, v5, 0x3a800000, v6
	v_mul_f32_e32 v7, 0x4b800000, v5
	v_cmp_gt_f32_e32 vcc, s3, v5
	s_nop 1
	v_cndmask_b32_e32 v5, v5, v7, vcc
	v_rsq_f32_e32 v5, v5
	s_nop 0
	v_mul_f32_e32 v7, 0x45800000, v5
	v_cndmask_b32_e32 v20, v5, v7, vcc
	v_pk_mul_f32 v[192:193], v[112:113], v[20:21] op_sel_hi:[1,0]
	v_pk_mul_f32 v[194:195], v[114:115], v[20:21] op_sel_hi:[1,0]
	v_pk_mul_f32 v[192:193], v[48:49], v[192:193]
	v_pk_mul_f32 v[194:195], v[50:51], v[194:195]
	global_store_dwordx4 v[12:13], v[192:195], off
	v_pk_mul_f32 v[196:197], v[116:117], v[20:21] op_sel_hi:[1,0]
	v_pk_mul_f32 v[198:199], v[118:119], v[20:21] op_sel_hi:[1,0]
	v_pk_mul_f32 v[196:197], v[52:53], v[196:197]
	v_pk_mul_f32 v[198:199], v[54:55], v[198:199]
	global_store_dwordx4 v[12:13], v[196:199], off offset:1024
	v_pk_mul_f32 v[200:201], v[120:121], v[20:21] op_sel_hi:[1,0]
	v_pk_mul_f32 v[202:203], v[122:123], v[20:21] op_sel_hi:[1,0]
	v_pk_mul_f32 v[200:201], v[56:57], v[200:201]
	v_pk_mul_f32 v[202:203], v[58:59], v[202:203]
	global_store_dwordx4 v[12:13], v[200:203], off offset:2048
	v_pk_mul_f32 v[204:205], v[124:125], v[20:21] op_sel_hi:[1,0]
	v_pk_mul_f32 v[206:207], v[126:127], v[20:21] op_sel_hi:[1,0]
	v_pk_mul_f32 v[204:205], v[60:61], v[204:205]
	v_pk_mul_f32 v[206:207], v[62:63], v[206:207]
	global_store_dwordx4 v[12:13], v[204:207], off offset:3072
	v_lshl_add_u64 v[12:13], v[12:13], 0, s[100:101]
	s_waitcnt vmcnt(8)
	v_add_f32_e32 v14, v128, v129
	v_add_f32_e32 v5, v130, v131
	v_add_f32_e32 v14, v14, v5
	v_add_f32_e32 v15, v132, v133
	v_add_f32_e32 v5, v134, v135
	v_add_f32_e32 v15, v15, v5
	v_add_f32_e32 v16, v136, v137
	v_add_f32_e32 v5, v138, v139
	v_add_f32_e32 v16, v16, v5
	v_add_f32_e32 v17, v140, v141
	v_add_f32_e32 v5, v142, v143
	v_add_f32_e32 v17, v17, v5
	v_add_f32_e32 v5, v14, v15
	v_add_f32_e32 v5, v5, v16
	v_add_f32_e32 v5, v5, v17
	v_fmamk_f32 v5, v5, 0x3a800000, v6
	v_mul_f32_e32 v7, 0x4b800000, v5
	v_cmp_gt_f32_e32 vcc, s3, v5
	s_nop 1
	v_cndmask_b32_e32 v5, v5, v7, vcc
	v_rsq_f32_e32 v5, v5
	s_nop 0
	v_mul_f32_e32 v7, 0x45800000, v5
	v_cndmask_b32_e32 v20, v5, v7, vcc
	v_pk_mul_f32 v[24:25], v[144:145], v[20:21] op_sel_hi:[1,0]
	v_pk_mul_f32 v[26:27], v[146:147], v[20:21] op_sel_hi:[1,0]
	v_pk_mul_f32 v[24:25], v[48:49], v[24:25]
	v_pk_mul_f32 v[26:27], v[50:51], v[26:27]
	global_store_dwordx4 v[12:13], v[24:27], off
	v_pk_mul_f32 v[28:29], v[148:149], v[20:21] op_sel_hi:[1,0]
	v_pk_mul_f32 v[30:31], v[150:151], v[20:21] op_sel_hi:[1,0]
	v_pk_mul_f32 v[28:29], v[52:53], v[28:29]
	v_pk_mul_f32 v[30:31], v[54:55], v[30:31]
	global_store_dwordx4 v[12:13], v[28:31], off offset:1024
	v_pk_mul_f32 v[32:33], v[152:153], v[20:21] op_sel_hi:[1,0]
	v_pk_mul_f32 v[34:35], v[154:155], v[20:21] op_sel_hi:[1,0]
	v_pk_mul_f32 v[32:33], v[56:57], v[32:33]
	v_pk_mul_f32 v[34:35], v[58:59], v[34:35]
	global_store_dwordx4 v[12:13], v[32:35], off offset:2048
	v_pk_mul_f32 v[36:37], v[156:157], v[20:21] op_sel_hi:[1,0]
	v_pk_mul_f32 v[38:39], v[158:159], v[20:21] op_sel_hi:[1,0]
	v_pk_mul_f32 v[36:37], v[60:61], v[36:37]
	v_pk_mul_f32 v[38:39], v[62:63], v[38:39]
	global_store_dwordx4 v[12:13], v[36:39], off offset:3072
	v_lshl_add_u64 v[12:13], v[12:13], 0, s[100:101]
	s_waitcnt vmcnt(0)
	v_add_f32_e32 v14, v160, v161
	v_add_f32_e32 v5, v162, v163
	v_add_f32_e32 v14, v14, v5
	v_add_f32_e32 v15, v164, v165
	v_add_f32_e32 v5, v166, v167
	v_add_f32_e32 v15, v15, v5
	v_add_f32_e32 v16, v168, v169
	v_add_f32_e32 v5, v170, v171
	v_add_f32_e32 v16, v16, v5
	v_add_f32_e32 v17, v172, v173
	v_add_f32_e32 v5, v174, v175
	v_add_f32_e32 v17, v17, v5
	v_add_f32_e32 v5, v14, v15
	v_add_f32_e32 v5, v5, v16
	v_add_f32_e32 v5, v5, v17
	v_fmamk_f32 v5, v5, 0x3a800000, v6
	v_mul_f32_e32 v7, 0x4b800000, v5
	v_cmp_gt_f32_e32 vcc, s3, v5
	s_nop 1
	v_cndmask_b32_e32 v5, v5, v7, vcc
	v_rsq_f32_e32 v5, v5
	s_nop 0
	v_mul_f32_e32 v7, 0x45800000, v5
	v_cndmask_b32_e32 v20, v5, v7, vcc
	v_pk_mul_f32 v[192:193], v[176:177], v[20:21] op_sel_hi:[1,0]
	v_pk_mul_f32 v[194:195], v[178:179], v[20:21] op_sel_hi:[1,0]
	v_pk_mul_f32 v[192:193], v[48:49], v[192:193]
	v_pk_mul_f32 v[194:195], v[50:51], v[194:195]
	global_store_dwordx4 v[12:13], v[192:195], off
	v_pk_mul_f32 v[196:197], v[180:181], v[20:21] op_sel_hi:[1,0]
	v_pk_mul_f32 v[198:199], v[182:183], v[20:21] op_sel_hi:[1,0]
	v_pk_mul_f32 v[196:197], v[52:53], v[196:197]
	v_pk_mul_f32 v[198:199], v[54:55], v[198:199]
	global_store_dwordx4 v[12:13], v[196:199], off offset:1024
	v_pk_mul_f32 v[200:201], v[184:185], v[20:21] op_sel_hi:[1,0]
	v_pk_mul_f32 v[202:203], v[186:187], v[20:21] op_sel_hi:[1,0]
	v_pk_mul_f32 v[200:201], v[56:57], v[200:201]
	v_pk_mul_f32 v[202:203], v[58:59], v[202:203]
	global_store_dwordx4 v[12:13], v[200:203], off offset:2048
	v_pk_mul_f32 v[204:205], v[188:189], v[20:21] op_sel_hi:[1,0]
	v_pk_mul_f32 v[206:207], v[190:191], v[20:21] op_sel_hi:[1,0]
	v_pk_mul_f32 v[204:205], v[60:61], v[204:205]
	v_pk_mul_f32 v[206:207], v[62:63], v[206:207]
	global_store_dwordx4 v[12:13], v[204:207], off offset:3072
	v_lshl_add_u64 v[12:13], v[12:13], 0, s[100:101]
	s_endpgm
